# no grid barrier between scanC and the Q/K projection GEMMs (independent phases)
# speedup vs baseline: 1.0056x; 1.0056x over previous
; #define otid() otid_impl(w0)
; #define LAS __attribute__((address_space(3)))
; __device__ __forceinline__ unsigned xb_xcc_id() { return (unsigned)__builtin_amdgcn_s_getreg((3 << 11) | 20) & 0xFu; }
; __device__ __forceinline__ void xcd_barrier(unsigned* bar_, volatile LAS unsigned* st_, int tid) {
;   XcdBarrier b; b.bar = bar_; b.st = st_; b.x = xb_xcc_id();
;   asm volatile("s_waitcnt vmcnt(0)" ::: "memory");
;   __syncthreads();
;   if (tid == 0) {
;     unsigned* bar = b.bar;
;     __builtin_amdgcn_s_waitcnt(0);
;     unsigned nloc = b.st[0], nx = b.st[1];
;     if (nloc == 0u) { xcd_barrier_complete(bar, b.x, nloc, nx); b.st[0] = nloc; b.st[1] = nx; }
; __global__ void __launch_bounds__(NTHREADS) mk(Params p, int ph0, int ph1) {
;     ...
;   for (int ph = ph0; ph < ph1; ++ph) {
;     run_phase(p, ph, shm, w0);
;     if (ph + 1 < ph1) {
;       { const int tid = otid(); xcd_barrier(p.bar, (volatile LAS unsigned*)&xb_words, tid); }
.LBB0_996:
	v_mbcnt_lo_u32_b32 v0, -1, 0
	v_mbcnt_hi_u32_b32 v0, -1, v0
	s_getreg_b32 s2, hwreg(HW_REG_XCC_ID, 0, 4)
	s_waitcnt vmcnt(0)
	v_readlane_b32 s0, v250, 1
	s_waitcnt lgkmcnt(0)
	s_barrier
	v_cmp_eq_u32_e32 vcc, s0, v0
	v_readlane_b32 s98, v250, 4
	s_sub_i32 s98, s98, 2
	s_mul_i32 s99, s98, 0xcccd
	s_lshr_b32 s99, s99, 19
	s_mul_i32 s99, s99, 10
	s_sub_i32 s99, s98, s99
	s_cmp_eq_u32 s99, 4
	s_cselect_b64 vcc, 0, vcc
	s_and_saveexec_b64 s[0:1], vcc
	s_cbranch_execnz .LBB0_997
	s_getpc_b64 s[98:99]
